# phase 2 rope epilogue: cos/sin tables of both row halves loaded up front
# baseline (speedup 1.0000x reference)
.Lp2_rope:
	v_mul_lo_u32 v66, v64, s14
	v_lshl_add_u32 v66, v65, 3, v66
	s_lshl_b32 s15, s14, 5
	v_add_u32_e32 v67, s15, v66
	v_lshlrev_b32_e32 v68, 7, v64
	v_lshl_add_u32 v68, v65, 4, v68
	v_add_u32_e32 v69, 0x1000, v68
	s_lshl_b32 s33, s6, 7
	s_add_u32 s34, s33, 0xda00000
	s_add_u32 s68, s88, s34
	s_addc_u32 s69, s89, 0
	s_add_u32 s34, s33, 0xdc00000
	s_add_u32 s70, s88, s34
	s_addc_u32 s71, s89, 0
	global_load_dwordx4 v[96:99], v68, s[68:69]
	global_load_dwordx4 v[112:115], v68, s[70:71]
	global_load_dwordx4 v[100:103], v68, s[68:69] offset:32
	global_load_dwordx4 v[116:119], v68, s[70:71] offset:32
	global_load_dwordx4 v[104:107], v68, s[68:69] offset:64
	global_load_dwordx4 v[120:123], v68, s[70:71] offset:64
	global_load_dwordx4 v[108:111], v68, s[68:69] offset:96
	global_load_dwordx4 v[124:127], v68, s[70:71] offset:96
	global_load_dwordx4 v[128:131], v69, s[68:69]
	global_load_dwordx4 v[144:147], v69, s[70:71]
	global_load_dwordx4 v[132:135], v69, s[68:69] offset:32
	global_load_dwordx4 v[148:151], v69, s[70:71] offset:32
	global_load_dwordx4 v[136:139], v69, s[68:69] offset:64
	global_load_dwordx4 v[152:155], v69, s[70:71] offset:64
	global_load_dwordx4 v[140:143], v69, s[68:69] offset:96
	global_load_dwordx4 v[156:159], v69, s[70:71] offset:96
	s_waitcnt vmcnt(14)
	v_mul_f32_e32 v70, v32, v112
	v_mul_f32_e32 v71, v33, v113
	v_mul_f32_e32 v72, v34, v114
	v_mul_f32_e32 v73, v35, v115
	v_mul_f32_e32 v74, v48, v112
	v_mul_f32_e32 v75, v49, v113
	v_mul_f32_e32 v76, v50, v114
	v_mul_f32_e32 v77, v51, v115
	v_fma_f32 v70, v48, v96, -v70
	v_fma_f32 v71, v49, v97, -v71
	v_fma_f32 v72, v50, v98, -v72
	v_fma_f32 v73, v51, v99, -v73
	v_fmac_f32_e32 v74, v32, v96
	v_fmac_f32_e32 v75, v33, v97
	v_fmac_f32_e32 v76, v34, v98
	v_fmac_f32_e32 v77, v35, v99
	v_cvt_pk_bf16_f32 v78, v70, v71
	v_cvt_pk_bf16_f32 v79, v72, v73
	v_cvt_pk_bf16_f32 v80, v74, v75
	v_cvt_pk_bf16_f32 v81, v76, v77
	global_store_dwordx2 v66, v[78:79], s[40:41]
	global_store_dwordx2 v66, v[80:81], s[40:41] offset:64
	s_waitcnt vmcnt(14)
	v_mul_f32_e32 v70, v36, v116
	v_mul_f32_e32 v71, v37, v117
	v_mul_f32_e32 v72, v38, v118
	v_mul_f32_e32 v73, v39, v119
	v_mul_f32_e32 v74, v52, v116
	v_mul_f32_e32 v75, v53, v117
	v_mul_f32_e32 v76, v54, v118
	v_mul_f32_e32 v77, v55, v119
	v_fma_f32 v70, v52, v100, -v70
	v_fma_f32 v71, v53, v101, -v71
	v_fma_f32 v72, v54, v102, -v72
	v_fma_f32 v73, v55, v103, -v73
	v_fmac_f32_e32 v74, v36, v100
	v_fmac_f32_e32 v75, v37, v101
	v_fmac_f32_e32 v76, v38, v102
	v_fmac_f32_e32 v77, v39, v103
	v_cvt_pk_bf16_f32 v82, v70, v71
	v_cvt_pk_bf16_f32 v83, v72, v73
	v_cvt_pk_bf16_f32 v84, v74, v75
	v_cvt_pk_bf16_f32 v85, v76, v77
	global_store_dwordx2 v66, v[82:83], s[40:41] offset:16
	global_store_dwordx2 v66, v[84:85], s[40:41] offset:80
	s_waitcnt vmcnt(14)
	v_mul_f32_e32 v70, v40, v120
	v_mul_f32_e32 v71, v41, v121
	v_mul_f32_e32 v72, v42, v122
	v_mul_f32_e32 v73, v43, v123
	v_mul_f32_e32 v74, v56, v120
	v_mul_f32_e32 v75, v57, v121
	v_mul_f32_e32 v76, v58, v122
	v_mul_f32_e32 v77, v59, v123
	v_fma_f32 v70, v56, v104, -v70
	v_fma_f32 v71, v57, v105, -v71
	v_fma_f32 v72, v58, v106, -v72
	v_fma_f32 v73, v59, v107, -v73
	v_fmac_f32_e32 v74, v40, v104
	v_fmac_f32_e32 v75, v41, v105
	v_fmac_f32_e32 v76, v42, v106
	v_fmac_f32_e32 v77, v43, v107
	v_cvt_pk_bf16_f32 v78, v70, v71
	v_cvt_pk_bf16_f32 v79, v72, v73
	v_cvt_pk_bf16_f32 v80, v74, v75
	v_cvt_pk_bf16_f32 v81, v76, v77
	global_store_dwordx2 v66, v[78:79], s[40:41] offset:32
	global_store_dwordx2 v66, v[80:81], s[40:41] offset:96
	s_waitcnt vmcnt(14)
	v_mul_f32_e32 v70, v44, v124
	v_mul_f32_e32 v71, v45, v125
	v_mul_f32_e32 v72, v46, v126
	v_mul_f32_e32 v73, v47, v127
	v_mul_f32_e32 v74, v60, v124
	v_mul_f32_e32 v75, v61, v125
	v_mul_f32_e32 v76, v62, v126
	v_mul_f32_e32 v77, v63, v127
	v_fma_f32 v70, v60, v108, -v70
	v_fma_f32 v71, v61, v109, -v71
	v_fma_f32 v72, v62, v110, -v72
	v_fma_f32 v73, v63, v111, -v73
	v_fmac_f32_e32 v74, v44, v108
	v_fmac_f32_e32 v75, v45, v109
	v_fmac_f32_e32 v76, v46, v110
	v_fmac_f32_e32 v77, v47, v111
	v_cvt_pk_bf16_f32 v82, v70, v71
	v_cvt_pk_bf16_f32 v83, v72, v73
	v_cvt_pk_bf16_f32 v84, v74, v75
	v_cvt_pk_bf16_f32 v85, v76, v77
	global_store_dwordx2 v66, v[82:83], s[40:41] offset:48
	global_store_dwordx2 v66, v[84:85], s[40:41] offset:112
	s_waitcnt vmcnt(14)
	v_mul_f32_e32 v70, v0, v144
	v_mul_f32_e32 v71, v1, v145
	v_mul_f32_e32 v72, v2, v146
	v_mul_f32_e32 v73, v3, v147
	v_mul_f32_e32 v74, v16, v144
	v_mul_f32_e32 v75, v17, v145
	v_mul_f32_e32 v76, v18, v146
	v_mul_f32_e32 v77, v19, v147
	v_fma_f32 v70, v16, v128, -v70
	v_fma_f32 v71, v17, v129, -v71
	v_fma_f32 v72, v18, v130, -v72
	v_fma_f32 v73, v19, v131, -v73
	v_fmac_f32_e32 v74, v0, v128
	v_fmac_f32_e32 v75, v1, v129
	v_fmac_f32_e32 v76, v2, v130
	v_fmac_f32_e32 v77, v3, v131
	v_cvt_pk_bf16_f32 v78, v70, v71
	v_cvt_pk_bf16_f32 v79, v72, v73
	v_cvt_pk_bf16_f32 v80, v74, v75
	v_cvt_pk_bf16_f32 v81, v76, v77
	global_store_dwordx2 v67, v[78:79], s[40:41]
	global_store_dwordx2 v67, v[80:81], s[40:41] offset:64
	s_waitcnt vmcnt(14)
	v_mul_f32_e32 v70, v4, v148
	v_mul_f32_e32 v71, v5, v149
	v_mul_f32_e32 v72, v6, v150
	v_mul_f32_e32 v73, v7, v151
	v_mul_f32_e32 v74, v20, v148
	v_mul_f32_e32 v75, v21, v149
	v_mul_f32_e32 v76, v22, v150
	v_mul_f32_e32 v77, v23, v151
	v_fma_f32 v70, v20, v132, -v70
	v_fma_f32 v71, v21, v133, -v71
	v_fma_f32 v72, v22, v134, -v72
	v_fma_f32 v73, v23, v135, -v73
	v_fmac_f32_e32 v74, v4, v132
	v_fmac_f32_e32 v75, v5, v133
	v_fmac_f32_e32 v76, v6, v134
	v_fmac_f32_e32 v77, v7, v135
	v_cvt_pk_bf16_f32 v82, v70, v71
	v_cvt_pk_bf16_f32 v83, v72, v73
	v_cvt_pk_bf16_f32 v84, v74, v75
	v_cvt_pk_bf16_f32 v85, v76, v77
	global_store_dwordx2 v67, v[82:83], s[40:41] offset:16
	global_store_dwordx2 v67, v[84:85], s[40:41] offset:80
	s_waitcnt vmcnt(14)
	v_mul_f32_e32 v70, v8, v152
	v_mul_f32_e32 v71, v9, v153
	v_mul_f32_e32 v72, v10, v154
	v_mul_f32_e32 v73, v11, v155
	v_mul_f32_e32 v74, v24, v152
	v_mul_f32_e32 v75, v25, v153
	v_mul_f32_e32 v76, v26, v154
	v_mul_f32_e32 v77, v27, v155
	v_fma_f32 v70, v24, v136, -v70
	v_fma_f32 v71, v25, v137, -v71
	v_fma_f32 v72, v26, v138, -v72
	v_fma_f32 v73, v27, v139, -v73
	v_fmac_f32_e32 v74, v8, v136
	v_fmac_f32_e32 v75, v9, v137
	v_fmac_f32_e32 v76, v10, v138
	v_fmac_f32_e32 v77, v11, v139
	v_cvt_pk_bf16_f32 v78, v70, v71
	v_cvt_pk_bf16_f32 v79, v72, v73
	v_cvt_pk_bf16_f32 v80, v74, v75
	v_cvt_pk_bf16_f32 v81, v76, v77
	global_store_dwordx2 v67, v[78:79], s[40:41] offset:32
	global_store_dwordx2 v67, v[80:81], s[40:41] offset:96
	s_waitcnt vmcnt(14)
	v_mul_f32_e32 v70, v12, v156
	v_mul_f32_e32 v71, v13, v157
	v_mul_f32_e32 v72, v14, v158
	v_mul_f32_e32 v73, v15, v159
	v_mul_f32_e32 v74, v28, v156
	v_mul_f32_e32 v75, v29, v157
	v_mul_f32_e32 v76, v30, v158
	v_mul_f32_e32 v77, v31, v159
	v_fma_f32 v70, v28, v140, -v70
	v_fma_f32 v71, v29, v141, -v71
	v_fma_f32 v72, v30, v142, -v72
	v_fma_f32 v73, v31, v143, -v73
	v_fmac_f32_e32 v74, v12, v140
	v_fmac_f32_e32 v75, v13, v141
	v_fmac_f32_e32 v76, v14, v142
	v_fmac_f32_e32 v77, v15, v143
	v_cvt_pk_bf16_f32 v82, v70, v71
	v_cvt_pk_bf16_f32 v83, v72, v73
	v_cvt_pk_bf16_f32 v84, v74, v75
	v_cvt_pk_bf16_f32 v85, v76, v77
	global_store_dwordx2 v67, v[82:83], s[40:41] offset:48
	global_store_dwordx2 v67, v[84:85], s[40:41] offset:112
	s_movk_i32 s34, 0x3fff
	s_branch .LBB0_341
